# c31: SSD sub-chunk staging reads the landing register sets directly (parity-specialised, no copies); per-sub-chunk scalar LDS reads issued right after the barrier
# speedup vs baseline: 1.0439x; 1.0039x over previous
; template <int PASS>
; __device__ void ssd_item(const Params& p, int item, int l, unsigned char* smem) {
;     ...
;     for (int si = 0; si < NSUB; ++si) {
;         const int scn = dir ? (NSUB - 1 - si) : si;
;         const int t0 = seg * SEGLEN + scn * TSUB;
;         __syncthreads();
;         u32x4 raw[5];
; #pragma unroll
;         for (int i = 0; i < 5; ++i) raw[i] = *(const u32x4*)(xb_ + ((unsigned)(t0 * 2048) + soff[i]));
;         const float* s_dt = s_dta + scn * TSUB; const float* s_c = s_cA + scn * TSUB; const float* s_rs = s_rsA + scn * TSUB; const float* s_wl = s_wlA + scn * TSUB;
;         const float stot = s_totA[scn];
;         segtot += stot;
.LBB0_737:
	s_add_i32 s99, s22, 2
	s_sub_i32 s100, 15, s99
	s_and_b64 s[24:25], vcc, exec
	s_cselect_b32 s101, s99, s100
	s_cselect_b32 s24, s22, s23
	s_lshl_b32 s101, s101, 16
	s_add_i32 s101, s101, s12
	s_waitcnt lgkmcnt(0)
	s_barrier
	v_lshl_add_u32 v85, s24, 7, v54
	s_mulk_i32 s24, 0xff84
	v_add_u32_e32 v84, s24, v85
	ds_read_b32 v84, v84 offset:54272
	v_lshl_add_u32 v150, v53, 2, v85
	ds_read_b32 v150, v150 offset:50688
	s_cmp_gt_u32 s22, 13
	s_cbranch_scc1 .Lssd1_tailwait
	s_waitcnt vmcnt(3)
	s_branch .Lssd1_w

; __device__ __forceinline__ unsigned pk2(float lo, float hi) { f32x2 v = {lo, hi}; bf16x2_t b = __builtin_convertvector(v, bf16x2_t); return __builtin_bit_cast(unsigned, b); }
; __device__ __forceinline__ float bflo(unsigned u) { return __uint_as_float(u << 16); }
; __device__ __forceinline__ float bfhi(unsigned u) { return __uint_as_float(u & 0xffff0000u); }
; template <int PASS>
; __device__ void ssd_item(const Params& p, int item, int l, unsigned char* smem) {
;     ...
;         for (int i = 0; i < 5; ++i) { const int u = tid + 256 * i, lrow = u / 40, ci = u % 40, lc = ci * 8; const u32x4 o = raw[i];
;             if (ci < 8) { *(u32x4*)(Xs + lrow * 72 + lc) = o; const float wl = s_wl[lrow];
;                 u32x4 o2; o2.x = pk2(bflo(o.x) * wl, bfhi(o.x) * wl); o2.y = pk2(bflo(o.y) * wl, bfhi(o.y) * wl); o2.z = pk2(bflo(o.z) * wl, bfhi(o.z) * wl); o2.w = pk2(bflo(o.w) * wl, bfhi(o.w) * wl);
;                 *(u32x4*)(Xws + lrow * 72 + lc) = o2; }
;             else if (ci < 24) *(u32x4*)(Bs + lrow * 136 + (lc - 64)) = o;
;             else *(u32x4*)(Cs + lrow * 136 + (lc - 192)) = o; }
.Lssd1_w:
	s_bitcmp1_b32 s22, 0
	s_cbranch_scc1 .Lssd1_odd
	ds_write_b128 v208, v[108:111]
	ds_write_b128 v208, v[112:115] offset:4352
	s_waitcnt lgkmcnt(2)
	v_lshlrev_b32_e32 v88, 16, v104
	v_and_b32_e32 v89, 0xffff0000, v104
	v_pk_mul_f32 v[88:89], v[150:151], v[88:89] op_sel_hi:[0,1]
	v_cvt_pk_bf16_f32 v104, v88, v89
	v_lshlrev_b32_e32 v88, 16, v105
	v_and_b32_e32 v89, 0xffff0000, v105
	v_pk_mul_f32 v[88:89], v[150:151], v[88:89] op_sel_hi:[0,1]
	v_cvt_pk_bf16_f32 v105, v88, v89
	v_lshlrev_b32_e32 v88, 16, v106
	v_and_b32_e32 v89, 0xffff0000, v106
	v_pk_mul_f32 v[88:89], v[150:151], v[88:89] op_sel_hi:[0,1]
	v_cvt_pk_bf16_f32 v106, v88, v89
	v_lshlrev_b32_e32 v88, 16, v107
	v_and_b32_e32 v89, 0xffff0000, v107
	v_pk_mul_f32 v[88:89], v[150:151], v[88:89] op_sel_hi:[0,1]
	v_cvt_pk_bf16_f32 v107, v88, v89
	ds_write_b128 v209, v[104:107] offset:22016
	s_cmp_gt_u32 s22, 13
	s_cbranch_scc1 .LBB0_736
	v_add_u32_e32 v146, s101, v63
	global_load_dwordx4 v[104:107], v146, s[64:65]
	v_add_u32_e32 v147, s101, v62
	global_load_dwordx4 v[108:111], v147, s[64:65]
	v_add_u32_e32 v146, s101, v61
	global_load_dwordx4 v[112:115], v146, s[64:65]
	s_branch .LBB0_736
.Lssd1_odd:
	ds_write_b128 v208, v[128:131]
	ds_write_b128 v208, v[132:135] offset:4352
	s_waitcnt lgkmcnt(2)
	v_lshlrev_b32_e32 v88, 16, v124
	v_and_b32_e32 v89, 0xffff0000, v124
	v_pk_mul_f32 v[88:89], v[150:151], v[88:89] op_sel_hi:[0,1]
	v_cvt_pk_bf16_f32 v124, v88, v89
	v_lshlrev_b32_e32 v88, 16, v125
	v_and_b32_e32 v89, 0xffff0000, v125
	v_pk_mul_f32 v[88:89], v[150:151], v[88:89] op_sel_hi:[0,1]
	v_cvt_pk_bf16_f32 v125, v88, v89
	v_lshlrev_b32_e32 v88, 16, v126
	v_and_b32_e32 v89, 0xffff0000, v126
	v_pk_mul_f32 v[88:89], v[150:151], v[88:89] op_sel_hi:[0,1]
	v_cvt_pk_bf16_f32 v126, v88, v89
	v_lshlrev_b32_e32 v88, 16, v127
	v_and_b32_e32 v89, 0xffff0000, v127
	v_pk_mul_f32 v[88:89], v[150:151], v[88:89] op_sel_hi:[0,1]
	v_cvt_pk_bf16_f32 v127, v88, v89
	ds_write_b128 v209, v[124:127] offset:22016
	s_cmp_gt_u32 s22, 13
	s_cbranch_scc1 .LBB0_736
	v_add_u32_e32 v146, s101, v63
	global_load_dwordx4 v[124:127], v146, s[64:65]
	v_add_u32_e32 v147, s101, v62
	global_load_dwordx4 v[128:131], v147, s[64:65]
	v_add_u32_e32 v146, s101, v61
	global_load_dwordx4 v[132:135], v146, s[64:65]
	s_branch .LBB0_736

; template <int PASS>
; __device__ void ssd_item(const Params& p, int item, int l, unsigned char* smem) {
;     ...
;     for (int si = 0; si < NSUB; ++si) {
;         const int scn = dir ? (NSUB - 1 - si) : si;
;         const int t0 = seg * SEGLEN + scn * TSUB;
;         __syncthreads();
;         u32x4 raw[5];
; #pragma unroll
;         for (int i = 0; i < 5; ++i) raw[i] = *(const u32x4*)(xb_ + ((unsigned)(t0 * 2048) + soff[i]));
;         const float* s_dt = s_dta + scn * TSUB; const float* s_c = s_cA + scn * TSUB; const float* s_rs = s_rsA + scn * TSUB; const float* s_wl = s_wlA + scn * TSUB;
;         const float stot = s_totA[scn];
;         segtot += stot;
.LBB0_914:
	s_sub_i32 s21, 15, s20
	s_add_i32 s99, s20, 2
	s_sub_i32 s100, 13, s20
	s_and_b64 s[22:23], exec, s[36:37]
	s_cselect_b32 s101, s99, s100
	s_cselect_b32 s22, s20, s21
	s_lshl_b32 s21, s22, 5
	s_add_i32 s21, s21, s12
	s_lshl_b32 s101, s101, 5
	s_add_i32 s101, s101, s12
	s_lshl_b32 s101, s101, 11
	s_waitcnt lgkmcnt(0)
	s_barrier
	v_lshl_add_u32 v96, s22, 7, v52
	s_mul_i32 s23, s22, 0xffffff84
	v_add_u32_e32 v97, s23, v96
	ds_read_b32 v95, v97 offset:54272
	v_lshl_add_u32 v164, v66, 2, v96
	ds_read_b32 v164, v164 offset:50688
	s_cmp_gt_u32 s20, 13
	s_cbranch_scc1 .Lssd3_tailwait
	s_waitcnt vmcnt(5)
	s_branch .Lssd3_w

; __device__ __forceinline__ unsigned pk2(float lo, float hi) { f32x2 v = {lo, hi}; bf16x2_t b = __builtin_convertvector(v, bf16x2_t); return __builtin_bit_cast(unsigned, b); }
; __device__ __forceinline__ float bflo(unsigned u) { return __uint_as_float(u << 16); }
; __device__ __forceinline__ float bfhi(unsigned u) { return __uint_as_float(u & 0xffff0000u); }
; template <int PASS>
; __device__ void ssd_item(const Params& p, int item, int l, unsigned char* smem) {
;     ...
;         for (int i = 0; i < 5; ++i) { const int u = tid + 256 * i, lrow = u / 40, ci = u % 40, lc = ci * 8; const u32x4 o = raw[i];
;             if (ci < 8) { *(u32x4*)(Xs + lrow * 72 + lc) = o; const float wl = s_wl[lrow];
;                 u32x4 o2; o2.x = pk2(bflo(o.x) * wl, bfhi(o.x) * wl); o2.y = pk2(bflo(o.y) * wl, bfhi(o.y) * wl); o2.z = pk2(bflo(o.z) * wl, bfhi(o.z) * wl); o2.w = pk2(bflo(o.w) * wl, bfhi(o.w) * wl);
;                 *(u32x4*)(Xws + lrow * 72 + lc) = o2; }
;             else if (ci < 24) *(u32x4*)(Bs + lrow * 136 + (lc - 64)) = o;
;             else *(u32x4*)(Cs + lrow * 136 + (lc - 192)) = o; }
.Lssd3_w:
	s_bitcmp1_b32 s20, 0
	s_cbranch_scc1 .Lssd3_odd
	ds_write_b128 v208, v[124:127]
	ds_write_b128 v208, v[128:131] offset:4352
	ds_write_b128 v208, v[132:135] offset:8704
	ds_write_b128 v208, v[136:139] offset:13056
	ds_write_b128 v209, v[120:123] offset:17408
	s_waitcnt lgkmcnt(5)
	v_lshlrev_b32_e32 v162, 16, v120
	v_and_b32_e32 v163, 0xffff0000, v120
	v_pk_mul_f32 v[162:163], v[164:165], v[162:163] op_sel_hi:[0,1]
	v_cvt_pk_bf16_f32 v120, v162, v163
	v_lshlrev_b32_e32 v162, 16, v121
	v_and_b32_e32 v163, 0xffff0000, v121
	v_pk_mul_f32 v[162:163], v[164:165], v[162:163] op_sel_hi:[0,1]
	v_cvt_pk_bf16_f32 v121, v162, v163
	v_lshlrev_b32_e32 v162, 16, v122
	v_and_b32_e32 v163, 0xffff0000, v122
	v_pk_mul_f32 v[162:163], v[164:165], v[162:163] op_sel_hi:[0,1]
	v_cvt_pk_bf16_f32 v122, v162, v163
	v_lshlrev_b32_e32 v162, 16, v123
	v_and_b32_e32 v163, 0xffff0000, v123
	v_pk_mul_f32 v[162:163], v[164:165], v[162:163] op_sel_hi:[0,1]
	v_cvt_pk_bf16_f32 v123, v162, v163
	ds_write_b128 v209, v[120:123] offset:22016
	s_cmp_gt_u32 s20, 13
	s_cbranch_scc1 .LBB0_925
	v_add_u32_e32 v140, s101, v70
	global_load_dwordx4 v[120:123], v140, s[96:97]
	v_add_u32_e32 v141, s101, v69
	global_load_dwordx4 v[124:127], v141, s[96:97]
	v_add_u32_e32 v140, s101, v68
	global_load_dwordx4 v[128:131], v140, s[96:97]
	v_add_u32_e32 v141, s101, v67
	global_load_dwordx4 v[132:135], v141, s[96:97]
	v_add_u32_e32 v140, s101, v71
	global_load_dwordx4 v[136:139], v140, s[96:97]
	s_branch .LBB0_925
.Lssd3_odd:
	ds_write_b128 v208, v[146:149]
	ds_write_b128 v208, v[150:153] offset:4352
	ds_write_b128 v208, v[154:157] offset:8704
	ds_write_b128 v208, v[158:161] offset:13056
	ds_write_b128 v209, v[142:145] offset:17408
	s_waitcnt lgkmcnt(5)
	v_lshlrev_b32_e32 v162, 16, v142
	v_and_b32_e32 v163, 0xffff0000, v142
	v_pk_mul_f32 v[162:163], v[164:165], v[162:163] op_sel_hi:[0,1]
	v_cvt_pk_bf16_f32 v142, v162, v163
	v_lshlrev_b32_e32 v162, 16, v143
	v_and_b32_e32 v163, 0xffff0000, v143
	v_pk_mul_f32 v[162:163], v[164:165], v[162:163] op_sel_hi:[0,1]
	v_cvt_pk_bf16_f32 v143, v162, v163
	v_lshlrev_b32_e32 v162, 16, v144
	v_and_b32_e32 v163, 0xffff0000, v144
	v_pk_mul_f32 v[162:163], v[164:165], v[162:163] op_sel_hi:[0,1]
	v_cvt_pk_bf16_f32 v144, v162, v163
	v_lshlrev_b32_e32 v162, 16, v145
	v_and_b32_e32 v163, 0xffff0000, v145
	v_pk_mul_f32 v[162:163], v[164:165], v[162:163] op_sel_hi:[0,1]
	v_cvt_pk_bf16_f32 v145, v162, v163
	ds_write_b128 v209, v[142:145] offset:22016
	s_cmp_gt_u32 s20, 13
	s_cbranch_scc1 .LBB0_925
	v_add_u32_e32 v140, s101, v70
	global_load_dwordx4 v[142:145], v140, s[96:97]
	v_add_u32_e32 v141, s101, v69
	global_load_dwordx4 v[146:149], v141, s[96:97]
	v_add_u32_e32 v140, s101, v68
	global_load_dwordx4 v[150:153], v140, s[96:97]
	v_add_u32_e32 v141, s101, v67
	global_load_dwordx4 v[154:157], v141, s[96:97]
	v_add_u32_e32 v140, s101, v71
	global_load_dwordx4 v[158:161], v140, s[96:97]
